# stack2 + nt on read-once gate/x epilogue loads (merge, out-proj), no-op adds dropped in P3 row-sum, SALU-formed M0 in the MLA q-expansion GEMM loop
# speedup vs baseline: 1.0055x; 1.0055x over previous
; template <int MODE>
; __device__ void attn_item(const Params& p, char* lds, int grp  , int b, int h, int qblk, int dry) {
;     ...
;         for (int r = 0; r < 16; r += 2) {
;           f32v2_t v = (f32v2_t){S[sub][r], S[sub][r + 1]} - m2;
;           v[0] = __builtin_amdgcn_exp2f(v[0]); v[1] = __builtin_amdgcn_exp2f(v[1]);
;           S[sub][r] = v[0]; S[sub][r + 1] = v[1]; ps2 += v;
;         }
;     ...
;       l += ps2[0] + ps2[1];
;     }
;     if (more) { if (MODE == 1) lwriteK((kt + 1) & 1); lwriteV((kt + 1) & 1); }
;     __syncthreads();
.LBB0_458:
	s_add_i32 s24, s24, 64
	v_add_f32_e32 v80, v82, v80
	v_add_f32_e32 v81, v83, v81
	s_add_u32 s50, s50, 0x22000
	v_add_f32_e32 v80, v84, v80
	v_add_f32_e32 v81, v85, v81
	s_addc_u32 s51, s51, 0
	v_add_f32_e32 v80, v86, v80
	v_add_f32_e32 v81, v87, v81
	s_cmp_eq_u32 s26, s3
	v_add_f32_e32 v80, v88, v80
	v_add_f32_e32 v81, v89, v81
	s_waitcnt lgkmcnt(0)
	v_add_f32_e32 v80, v90, v80
	v_add_f32_e32 v81, v91, v81
	s_barrier
	v_add_f32_e32 v80, v92, v80
	v_add_f32_e32 v81, v93, v81
	v_add_f32_e32 v80, v94, v80
	v_add_f32_e32 v81, v95, v81
	v_add_f32_e32 v64, v64, v80
	v_add_f32_e32 v65, v65, v81
	v_add_f32_e32 v64, v66, v64
	v_add_f32_e32 v65, v67, v65
	v_add_f32_e32 v64, v68, v64
	v_add_f32_e32 v65, v69, v65
	v_add_f32_e32 v64, v70, v64
	v_add_f32_e32 v65, v71, v65
	v_add_f32_e32 v64, v72, v64
	v_add_f32_e32 v65, v73, v65
	v_add_f32_e32 v64, v74, v64
	v_add_f32_e32 v65, v75, v65
	v_add_f32_e32 v64, v76, v64
	v_add_f32_e32 v65, v77, v65
	v_add_f32_e32 v64, v78, v64
	v_add_f32_e32 v65, v79, v65
	v_add_f32_e32 v64, v64, v65
	v_add_f32_e32 v161, v161, v64
	s_cbranch_scc1 .LBB0_460
	s_mov_b32 s27, s3
	s_branch .LBB0_448

; template <bool SW>
; __device__ __forceinline__ void gemm_mainloop(const bf16_t* __restrict__ A, int lda, const bf16_t* __restrict__ Bt, int ldb, int K,
;                                               f32x16 (&acc)[2][2], char* lds, int kstart) {
;     ...
;     if (more) {
;       char* d = ldst + ((kt + 1) & 1) * GEMM_BUF;
;       const int ko = ((kt + 1 + kstart) & (nk - 1)) * 64;
; #pragma unroll
;       for (int i = 0; i < 4; ++i) { glds16(ap[i] + ko, d + i * 1024); glds16(bp[i] + ko, d + 16384 + i * 1024); }
;     }
.LBB0_565:
	s_andn2_b64 vcc, exec, s[0:1]
	s_cbranch_vccnz .LBB0_562
	s_add_i32 s44, s43, 0x8000
	s_and_b32 s0, s44, 0x8000
	v_readfirstlane_b32 s1, v114
	s_and_b32 s10, s2, 0xc0
	s_lshl_b32 s10, s10, 1
	s_add_i32 s0, s0, s1
	s_mov_b32 m0, s0
	v_lshl_add_u64 v[108:109], v[92:93], 0, s[10:11]
	global_load_lds_dwordx4 v[108:109], off
	s_add_i32 m0, s0, 0x4000
	v_lshl_add_u64 v[108:109], v[94:95], 0, s[10:11]
	global_load_lds_dwordx4 v[108:109], off
	s_add_i32 m0, s0, 0x400
	v_lshl_add_u64 v[108:109], v[96:97], 0, s[10:11]
	global_load_lds_dwordx4 v[108:109], off
	s_add_i32 m0, s0, 0x4400
	v_lshl_add_u64 v[108:109], v[98:99], 0, s[10:11]
	global_load_lds_dwordx4 v[108:109], off
	s_add_i32 m0, s0, 0x800
	v_lshl_add_u64 v[108:109], v[100:101], 0, s[10:11]
	global_load_lds_dwordx4 v[108:109], off
	s_add_i32 m0, s0, 0x4800
	v_lshl_add_u64 v[108:109], v[102:103], 0, s[10:11]
	global_load_lds_dwordx4 v[108:109], off
	s_add_i32 m0, s0, 0xc00
	v_lshl_add_u64 v[108:109], v[104:105], 0, s[10:11]
	global_load_lds_dwordx4 v[108:109], off
	s_add_i32 m0, s0, 0x4c00
	v_lshl_add_u64 v[108:109], v[106:107], 0, s[10:11]
	global_load_lds_dwordx4 v[108:109], off
	s_branch .LBB0_562

; __device__ __forceinline__ unsigned pk2(float lo, float hi) { f32v2_t v = {lo, hi}; bf16v2_t r = __builtin_convertvector(v, bf16v2_t); return __builtin_bit_cast(unsigned, r); }
; __device__ __forceinline__ float bflo(unsigned w) { return __uint_as_float(w << 16); }
; __device__ __forceinline__ float bfhi(unsigned w) { return __uint_as_float(w & 0xffff0000u); }
; __device__ void phase_merge(const Params& p, char* lds) {
;     ...
;           const int tok = m0 + wr * 64 + i * 32 + l31b; const int cb = n0 + wc * 64 + j * 32;
;           const bf16_t* gp = gates + (size_t)tok * 2048 + 1024 + cb + 4 * hh;
;           bf16_t* op = mg + (size_t)tok * LDH + cb + 4 * hh;
; #pragma unroll
;           for (int g = 0; g < 4; ++g) {
;             const u32x2 gv = *(const u32x2*)(gp + 8 * g);
;             const u32x2 pv = *(const u32x2*)(op + 8 * g);
;             u32x2 w;
;             w.x = pk2(bflo(pv.x) + acc[i][j][4 * g] * bflo(gv.x), bfhi(pv.x) + acc[i][j][4 * g + 1] * bfhi(gv.x));
;             w.y = pk2(bflo(pv.y) + acc[i][j][4 * g + 2] * bflo(gv.y), bfhi(pv.y) + acc[i][j][4 * g + 3] * bfhi(gv.y));
;             *(u32x2*)(op + 8 * g) = w;
;           }
.LBB0_787:
	s_add_i32 s2, s2, 1
	v_and_b32_e32 v123, 63, v181
	v_lshrrev_b32_e32 v122, 6, v181
	v_and_b32_e32 v118, 31, v123
	v_lshrrev_b32_e32 v119, 5, v123
	v_mul_u32_u24_e32 v118, 0x110, v118
	v_lshlrev_b32_e32 v119, 4, v119
	v_mul_u32_u24_e32 v120, 0x2200, v122
	v_add3_u32 v118, v118, v119, v120
	v_add_u32_e32 v118, 0x8000, v118
	v_add_u32_e32 v119, 0x8000, v120
	v_lshrrev_b32_e32 v120, 3, v123
	v_and_b32_e32 v121, 7, v123
	v_mul_u32_u24_e32 v123, 0x110, v120
	v_add_u32_e32 v119, v119, v123
	v_lshl_add_u32 v119, v121, 5, v119
	v_readlane_b32 vcc_lo, v248, 4
	v_readlane_b32 vcc_hi, v248, 5
	s_lshl_b32 s0, s3, 12
	s_lshl_b32 s1, s44, 1
	s_add_i32 s0, s0, s1
	s_mul_i32 s10, s3, 0x880
	s_add_i32 s1, s1, s10
	s_add_i32 s1, s1, 0x1699e000
	v_lshrrev_b32_e32 v124, 1, v122
	v_mul_u32_u24_e32 v124, 0x40000, v124
	v_mul_u32_u24_e32 v126, 0x1000, v120
	v_add_u32_e32 v124, v124, v126
	v_and_b32_e32 v126, 1, v122
	v_mul_u32_u24_e32 v126, 0x80, v126
	v_lshl_add_u32 v126, v121, 4, v126
	v_add3_u32 v124, v124, v126, s0
	v_lshrrev_b32_e32 v125, 1, v122
	v_mul_u32_u24_e32 v125, 0x22000, v125
	v_mul_u32_u24_e32 v126, 0x880, v120
	v_add_u32_e32 v125, v125, v126
	v_and_b32_e32 v126, 1, v122
	v_mul_u32_u24_e32 v126, 0x80, v126
	v_lshl_add_u32 v126, v121, 4, v126
	v_add3_u32 v125, v125, v126, s1
	ds_write_b128 v118, v[48:51] offset:0
	ds_write_b128 v118, v[52:55] offset:32
	ds_write_b128 v118, v[56:59] offset:64
	ds_write_b128 v118, v[60:63] offset:96
	ds_write_b128 v118, v[32:35] offset:128
	ds_write_b128 v118, v[36:39] offset:160
	ds_write_b128 v118, v[40:43] offset:192
	ds_write_b128 v118, v[44:47] offset:224
	s_waitcnt lgkmcnt(0)
	global_load_dwordx4 v[84:87], v124, vcc offset:2048 nt
	v_add_u32_e32 v124, 0x8000, v124
	global_load_dwordx4 v[88:91], v124, vcc offset:2048 nt
	v_add_u32_e32 v124, 0x8000, v124
	global_load_dwordx4 v[92:95], v124, vcc offset:2048 nt
	v_add_u32_e32 v124, 0x8000, v124
	global_load_dwordx4 v[96:99], v124, vcc offset:2048 nt
	v_add_u32_e32 v124, 0x8000, v124
	v_mov_b32_e32 v126, v125
	global_load_dwordx4 v[48:51], v126, s[96:97]
	v_add_u32_e32 v126, 0x4400, v126
	global_load_dwordx4 v[52:55], v126, s[96:97]
	v_add_u32_e32 v126, 0x4400, v126
	global_load_dwordx4 v[56:59], v126, s[96:97]
	v_add_u32_e32 v126, 0x4400, v126
	global_load_dwordx4 v[60:63], v126, s[96:97]
	v_add_u32_e32 v126, 0x4400, v126
	ds_read_b128 v[32:35], v119 offset:0
	ds_read_b128 v[36:39], v119 offset:16
	ds_read_b128 v[40:43], v119 offset:2176
	ds_read_b128 v[44:47], v119 offset:2192
	s_waitcnt vmcnt(3) lgkmcnt(2)
	v_lshlrev_b32_e32 v127, 16, v84
	v_lshlrev_b32_e32 v128, 16, v48
	v_fma_f32 v32, v32, v127, v128
	v_and_b32_e32 v127, 0xffff0000, v84
	v_and_b32_e32 v128, 0xffff0000, v48
	v_fma_f32 v33, v33, v127, v128
	v_lshlrev_b32_e32 v127, 16, v85
	v_lshlrev_b32_e32 v128, 16, v49
	v_fma_f32 v34, v34, v127, v128
	v_and_b32_e32 v127, 0xffff0000, v85
	v_and_b32_e32 v128, 0xffff0000, v49
	v_fma_f32 v35, v35, v127, v128
	v_lshlrev_b32_e32 v127, 16, v86
	v_lshlrev_b32_e32 v128, 16, v50
	v_fma_f32 v36, v36, v127, v128
	v_and_b32_e32 v127, 0xffff0000, v86
	v_and_b32_e32 v128, 0xffff0000, v50
	v_fma_f32 v37, v37, v127, v128
	v_lshlrev_b32_e32 v127, 16, v87
	v_lshlrev_b32_e32 v128, 16, v51
	v_fma_f32 v38, v38, v127, v128
	v_and_b32_e32 v127, 0xffff0000, v87
	v_and_b32_e32 v128, 0xffff0000, v51
	v_fma_f32 v39, v39, v127, v128
	v_cvt_pk_bf16_f32 v32, v32, v33
	v_cvt_pk_bf16_f32 v33, v34, v35
	v_cvt_pk_bf16_f32 v34, v36, v37
	v_cvt_pk_bf16_f32 v35, v38, v39
	global_store_dwordx4 v125, v[32:35], s[96:97]
	v_add_u32_e32 v125, 0x4400, v125
	s_waitcnt vmcnt(3) lgkmcnt(0)
	v_lshlrev_b32_e32 v127, 16, v88
	v_lshlrev_b32_e32 v128, 16, v52
	v_fma_f32 v40, v40, v127, v128
	v_and_b32_e32 v127, 0xffff0000, v88
	v_and_b32_e32 v128, 0xffff0000, v52
	v_fma_f32 v41, v41, v127, v128
	v_lshlrev_b32_e32 v127, 16, v89
	v_lshlrev_b32_e32 v128, 16, v53
	v_fma_f32 v42, v42, v127, v128
	v_and_b32_e32 v127, 0xffff0000, v89
	v_and_b32_e32 v128, 0xffff0000, v53
	v_fma_f32 v43, v43, v127, v128
	v_lshlrev_b32_e32 v127, 16, v90
	v_lshlrev_b32_e32 v128, 16, v54
	v_fma_f32 v44, v44, v127, v128
	v_and_b32_e32 v127, 0xffff0000, v90
	v_and_b32_e32 v128, 0xffff0000, v54
	v_fma_f32 v45, v45, v127, v128
	v_lshlrev_b32_e32 v127, 16, v91
	v_lshlrev_b32_e32 v128, 16, v55
	v_fma_f32 v46, v46, v127, v128
	v_and_b32_e32 v127, 0xffff0000, v91
	v_and_b32_e32 v128, 0xffff0000, v55
	v_fma_f32 v47, v47, v127, v128
	v_cvt_pk_bf16_f32 v40, v40, v41
	v_cvt_pk_bf16_f32 v41, v42, v43
	v_cvt_pk_bf16_f32 v42, v44, v45
	v_cvt_pk_bf16_f32 v43, v46, v47
	global_store_dwordx4 v125, v[40:43], s[96:97]
	v_add_u32_e32 v125, 0x4400, v125
	ds_read_b128 v[32:35], v119 offset:4352
	ds_read_b128 v[36:39], v119 offset:4368
	ds_read_b128 v[40:43], v119 offset:6528
	ds_read_b128 v[44:47], v119 offset:6544
	s_waitcnt vmcnt(3) lgkmcnt(2)
	v_lshlrev_b32_e32 v127, 16, v92
	v_lshlrev_b32_e32 v128, 16, v56
	v_fma_f32 v32, v32, v127, v128
	v_and_b32_e32 v127, 0xffff0000, v92
	v_and_b32_e32 v128, 0xffff0000, v56
	v_fma_f32 v33, v33, v127, v128
	v_lshlrev_b32_e32 v127, 16, v93
	v_lshlrev_b32_e32 v128, 16, v57
	v_fma_f32 v34, v34, v127, v128
	v_and_b32_e32 v127, 0xffff0000, v93
	v_and_b32_e32 v128, 0xffff0000, v57
	v_fma_f32 v35, v35, v127, v128
	v_lshlrev_b32_e32 v127, 16, v94
	v_lshlrev_b32_e32 v128, 16, v58
	v_fma_f32 v36, v36, v127, v128
	v_and_b32_e32 v127, 0xffff0000, v94
	v_and_b32_e32 v128, 0xffff0000, v58
	v_fma_f32 v37, v37, v127, v128
	v_lshlrev_b32_e32 v127, 16, v95
	v_lshlrev_b32_e32 v128, 16, v59
	v_fma_f32 v38, v38, v127, v128
	v_and_b32_e32 v127, 0xffff0000, v95
	v_and_b32_e32 v128, 0xffff0000, v59
	v_fma_f32 v39, v39, v127, v128
	v_cvt_pk_bf16_f32 v32, v32, v33
	v_cvt_pk_bf16_f32 v33, v34, v35
	v_cvt_pk_bf16_f32 v34, v36, v37
	v_cvt_pk_bf16_f32 v35, v38, v39
	global_store_dwordx4 v125, v[32:35], s[96:97]
	v_add_u32_e32 v125, 0x4400, v125
	s_waitcnt vmcnt(3) lgkmcnt(0)
; __device__ __forceinline__ unsigned pk2(float lo, float hi) { f32v2_t v = {lo, hi}; bf16v2_t r = __builtin_convertvector(v, bf16v2_t); return __builtin_bit_cast(unsigned, r); }
; __device__ __forceinline__ float bflo(unsigned w) { return __uint_as_float(w << 16); }
; __device__ __forceinline__ float bfhi(unsigned w) { return __uint_as_float(w & 0xffff0000u); }
; __device__ void phase_merge(const Params& p, char* lds) {
;     ...
;           const int tok = m0 + wr * 64 + i * 32 + l31b; const int cb = n0 + wc * 64 + j * 32;
;           const bf16_t* gp = gates + (size_t)tok * 2048 + 1024 + cb + 4 * hh;
;           bf16_t* op = mg + (size_t)tok * LDH + cb + 4 * hh;
; #pragma unroll
;           for (int g = 0; g < 4; ++g) {
;             const u32x2 gv = *(const u32x2*)(gp + 8 * g);
;             const u32x2 pv = *(const u32x2*)(op + 8 * g);
;             u32x2 w;
;             w.x = pk2(bflo(pv.x) + acc[i][j][4 * g] * bflo(gv.x), bfhi(pv.x) + acc[i][j][4 * g + 1] * bfhi(gv.x));
;             w.y = pk2(bflo(pv.y) + acc[i][j][4 * g + 2] * bflo(gv.y), bfhi(pv.y) + acc[i][j][4 * g + 3] * bfhi(gv.y));
;             *(u32x2*)(op + 8 * g) = w;
;           }
; __device__ void phase_outproj(const Params& p, char* lds) {
;     ...
;     int mt, nt; if (!tile_at(260, 8, it, mt, nt)) break;
	v_lshlrev_b32_e32 v127, 16, v96
	v_lshlrev_b32_e32 v128, 16, v60
	v_fma_f32 v40, v40, v127, v128
	v_and_b32_e32 v127, 0xffff0000, v96
	v_and_b32_e32 v128, 0xffff0000, v60
	v_fma_f32 v41, v41, v127, v128
	v_lshlrev_b32_e32 v127, 16, v97
	v_lshlrev_b32_e32 v128, 16, v61
	v_fma_f32 v42, v42, v127, v128
	v_and_b32_e32 v127, 0xffff0000, v97
	v_and_b32_e32 v128, 0xffff0000, v61
	v_fma_f32 v43, v43, v127, v128
	v_lshlrev_b32_e32 v127, 16, v98
	v_lshlrev_b32_e32 v128, 16, v62
	v_fma_f32 v44, v44, v127, v128
	v_and_b32_e32 v127, 0xffff0000, v98
	v_and_b32_e32 v128, 0xffff0000, v62
	v_fma_f32 v45, v45, v127, v128
	v_lshlrev_b32_e32 v127, 16, v99
	v_lshlrev_b32_e32 v128, 16, v63
	v_fma_f32 v46, v46, v127, v128
	v_and_b32_e32 v127, 0xffff0000, v99
	v_and_b32_e32 v128, 0xffff0000, v63
	v_fma_f32 v47, v47, v127, v128
	v_cvt_pk_bf16_f32 v40, v40, v41
	v_cvt_pk_bf16_f32 v41, v42, v43
	v_cvt_pk_bf16_f32 v42, v44, v45
	v_cvt_pk_bf16_f32 v43, v46, v47
	global_store_dwordx4 v125, v[40:43], s[96:97]
	v_add_u32_e32 v125, 0x4400, v125
	ds_write_b128 v118, v[16:19] offset:0
	ds_write_b128 v118, v[20:23] offset:32
	ds_write_b128 v118, v[24:27] offset:64
	ds_write_b128 v118, v[28:31] offset:96
	ds_write_b128 v118, v[0:3] offset:128
	ds_write_b128 v118, v[4:7] offset:160
	ds_write_b128 v118, v[8:11] offset:192
	ds_write_b128 v118, v[12:15] offset:224
	s_waitcnt lgkmcnt(0)
	global_load_dwordx4 v[84:87], v124, vcc offset:2048 nt
	v_add_u32_e32 v124, 0x8000, v124
	global_load_dwordx4 v[88:91], v124, vcc offset:2048 nt
	v_add_u32_e32 v124, 0x8000, v124
	global_load_dwordx4 v[92:95], v124, vcc offset:2048 nt
	v_add_u32_e32 v124, 0x8000, v124
	global_load_dwordx4 v[96:99], v124, vcc offset:2048 nt
	v_add_u32_e32 v124, 0x8000, v124
	v_mov_b32_e32 v126, v125
	global_load_dwordx4 v[16:19], v126, s[96:97]
	v_add_u32_e32 v126, 0x4400, v126
	global_load_dwordx4 v[20:23], v126, s[96:97]
	v_add_u32_e32 v126, 0x4400, v126
	global_load_dwordx4 v[24:27], v126, s[96:97]
	v_add_u32_e32 v126, 0x4400, v126
	global_load_dwordx4 v[28:31], v126, s[96:97]
	v_add_u32_e32 v126, 0x4400, v126
	ds_read_b128 v[0:3], v119 offset:0
	ds_read_b128 v[4:7], v119 offset:16
	ds_read_b128 v[8:11], v119 offset:2176
	ds_read_b128 v[12:15], v119 offset:2192
	s_waitcnt vmcnt(3) lgkmcnt(2)
	v_lshlrev_b32_e32 v127, 16, v84
	v_lshlrev_b32_e32 v128, 16, v16
	v_fma_f32 v0, v0, v127, v128
	v_and_b32_e32 v127, 0xffff0000, v84
	v_and_b32_e32 v128, 0xffff0000, v16
	v_fma_f32 v1, v1, v127, v128
	v_lshlrev_b32_e32 v127, 16, v85
	v_lshlrev_b32_e32 v128, 16, v17
	v_fma_f32 v2, v2, v127, v128
	v_and_b32_e32 v127, 0xffff0000, v85
	v_and_b32_e32 v128, 0xffff0000, v17
	v_fma_f32 v3, v3, v127, v128
	v_lshlrev_b32_e32 v127, 16, v86
	v_lshlrev_b32_e32 v128, 16, v18
	v_fma_f32 v4, v4, v127, v128
	v_and_b32_e32 v127, 0xffff0000, v86
	v_and_b32_e32 v128, 0xffff0000, v18
	v_fma_f32 v5, v5, v127, v128
	v_lshlrev_b32_e32 v127, 16, v87
	v_lshlrev_b32_e32 v128, 16, v19
	v_fma_f32 v6, v6, v127, v128
	v_and_b32_e32 v127, 0xffff0000, v87
	v_and_b32_e32 v128, 0xffff0000, v19
	v_fma_f32 v7, v7, v127, v128
	v_cvt_pk_bf16_f32 v0, v0, v1
	v_cvt_pk_bf16_f32 v1, v2, v3
	v_cvt_pk_bf16_f32 v2, v4, v5
	v_cvt_pk_bf16_f32 v3, v6, v7
	global_store_dwordx4 v125, v[0:3], s[96:97]
	v_add_u32_e32 v125, 0x4400, v125
	s_waitcnt vmcnt(3) lgkmcnt(0)
	v_lshlrev_b32_e32 v127, 16, v88
	v_lshlrev_b32_e32 v128, 16, v20
	v_fma_f32 v8, v8, v127, v128
	v_and_b32_e32 v127, 0xffff0000, v88
	v_and_b32_e32 v128, 0xffff0000, v20
	v_fma_f32 v9, v9, v127, v128
	v_lshlrev_b32_e32 v127, 16, v89
	v_lshlrev_b32_e32 v128, 16, v21
	v_fma_f32 v10, v10, v127, v128
	v_and_b32_e32 v127, 0xffff0000, v89
	v_and_b32_e32 v128, 0xffff0000, v21
	v_fma_f32 v11, v11, v127, v128
	v_lshlrev_b32_e32 v127, 16, v90
	v_lshlrev_b32_e32 v128, 16, v22
	v_fma_f32 v12, v12, v127, v128
	v_and_b32_e32 v127, 0xffff0000, v90
	v_and_b32_e32 v128, 0xffff0000, v22
	v_fma_f32 v13, v13, v127, v128
	v_lshlrev_b32_e32 v127, 16, v91
	v_lshlrev_b32_e32 v128, 16, v23
	v_fma_f32 v14, v14, v127, v128
	v_and_b32_e32 v127, 0xffff0000, v91
	v_and_b32_e32 v128, 0xffff0000, v23
	v_fma_f32 v15, v15, v127, v128
	v_cvt_pk_bf16_f32 v8, v8, v9
	v_cvt_pk_bf16_f32 v9, v10, v11
	v_cvt_pk_bf16_f32 v10, v12, v13
	v_cvt_pk_bf16_f32 v11, v14, v15
	global_store_dwordx4 v125, v[8:11], s[96:97]
	v_add_u32_e32 v125, 0x4400, v125
	ds_read_b128 v[0:3], v119 offset:4352
	ds_read_b128 v[4:7], v119 offset:4368
	ds_read_b128 v[8:11], v119 offset:6528
	ds_read_b128 v[12:15], v119 offset:6544
	s_waitcnt vmcnt(3) lgkmcnt(2)
	v_lshlrev_b32_e32 v127, 16, v92
	v_lshlrev_b32_e32 v128, 16, v24
	v_fma_f32 v0, v0, v127, v128
	v_and_b32_e32 v127, 0xffff0000, v92
	v_and_b32_e32 v128, 0xffff0000, v24
	v_fma_f32 v1, v1, v127, v128
	v_lshlrev_b32_e32 v127, 16, v93
	v_lshlrev_b32_e32 v128, 16, v25
	v_fma_f32 v2, v2, v127, v128
	v_and_b32_e32 v127, 0xffff0000, v93
	v_and_b32_e32 v128, 0xffff0000, v25
	v_fma_f32 v3, v3, v127, v128
	v_lshlrev_b32_e32 v127, 16, v94
	v_lshlrev_b32_e32 v128, 16, v26
	v_fma_f32 v4, v4, v127, v128
	v_and_b32_e32 v127, 0xffff0000, v94
	v_and_b32_e32 v128, 0xffff0000, v26
	v_fma_f32 v5, v5, v127, v128
	v_lshlrev_b32_e32 v127, 16, v95
	v_lshlrev_b32_e32 v128, 16, v27
	v_fma_f32 v6, v6, v127, v128
	v_and_b32_e32 v127, 0xffff0000, v95
	v_and_b32_e32 v128, 0xffff0000, v27
	v_fma_f32 v7, v7, v127, v128
	v_cvt_pk_bf16_f32 v0, v0, v1
	v_cvt_pk_bf16_f32 v1, v2, v3
	v_cvt_pk_bf16_f32 v2, v4, v5
	v_cvt_pk_bf16_f32 v3, v6, v7
	global_store_dwordx4 v125, v[0:3], s[96:97]
	v_add_u32_e32 v125, 0x4400, v125
	s_waitcnt vmcnt(3) lgkmcnt(0)
	v_lshlrev_b32_e32 v127, 16, v96
	v_lshlrev_b32_e32 v128, 16, v28
	v_fma_f32 v8, v8, v127, v128
	v_and_b32_e32 v127, 0xffff0000, v96
	v_and_b32_e32 v128, 0xffff0000, v28
	v_fma_f32 v9, v9, v127, v128
	v_lshlrev_b32_e32 v127, 16, v97
	v_lshlrev_b32_e32 v128, 16, v29
	v_fma_f32 v10, v10, v127, v128
	v_and_b32_e32 v127, 0xffff0000, v97
	v_and_b32_e32 v128, 0xffff0000, v29
	v_fma_f32 v11, v11, v127, v128
	v_lshlrev_b32_e32 v127, 16, v98
	v_lshlrev_b32_e32 v128, 16, v30
	v_fma_f32 v12, v12, v127, v128
	v_and_b32_e32 v127, 0xffff0000, v98
	v_and_b32_e32 v128, 0xffff0000, v30
	v_fma_f32 v13, v13, v127, v128
	v_lshlrev_b32_e32 v127, 16, v99
	v_lshlrev_b32_e32 v128, 16, v31
	v_fma_f32 v14, v14, v127, v128
	v_and_b32_e32 v127, 0xffff0000, v99
	v_and_b32_e32 v128, 0xffff0000, v31
	v_fma_f32 v15, v15, v127, v128
	v_cvt_pk_bf16_f32 v8, v8, v9
	v_cvt_pk_bf16_f32 v9, v10, v11
	v_cvt_pk_bf16_f32 v10, v12, v13
	v_cvt_pk_bf16_f32 v11, v14, v15
	global_store_dwordx4 v125, v[8:11], s[96:97]
	v_add_u32_e32 v125, 0x4400, v125
	s_mul_i32 s0, s2, s12
	s_add_i32 s0, s0, s33
	s_cmp_lt_i32 s0, s17
	s_cbranch_scc0 .LBB0_800

; __device__ __forceinline__ unsigned pk2(float lo, float hi) { f32v2_t v = {lo, hi}; bf16v2_t r = __builtin_convertvector(v, bf16v2_t); return __builtin_bit_cast(unsigned, r); }
; __device__ __forceinline__ float bflo(unsigned w) { return __uint_as_float(w << 16); }
; __device__ __forceinline__ float bfhi(unsigned w) { return __uint_as_float(w & 0xffff0000u); }
; __device__ void phase_merge(const Params& p, char* lds) {
;     ...
;           const int tok = m0 + wr * 64 + i * 32 + l31; const int cb = n0 + wc * 64 + j * 32;
;           const bf16_t* gp = gates + (size_t)tok * 2048 + cb + 4 * hh;
;           bf16_t* op = mg + (size_t)tok * LDH + cb + 4 * hh;
; #pragma unroll
;           for (int g = 0; g < 4; ++g) {
;             const u32x2 gv = *(const u32x2*)(gp + 8 * g);
;             u32x2 w;
;             w.x = pk2(acc[i][j][4 * g] * bflo(gv.x), acc[i][j][4 * g + 1] * bfhi(gv.x));
;             w.y = pk2(acc[i][j][4 * g + 2] * bflo(gv.y), acc[i][j][4 * g + 3] * bfhi(gv.y));
;             *(u32x2*)(op + 8 * g) = w;
;           }
.LBB0_794:
	v_and_b32_e32 v123, 63, v181
	v_lshrrev_b32_e32 v122, 6, v181
	v_and_b32_e32 v118, 31, v123
	v_lshrrev_b32_e32 v119, 5, v123
	v_mul_u32_u24_e32 v118, 0x110, v118
	v_lshlrev_b32_e32 v119, 4, v119
	v_mul_u32_u24_e32 v120, 0x2200, v122
	v_add3_u32 v118, v118, v119, v120
	v_add_u32_e32 v118, 0x8000, v118
	v_add_u32_e32 v119, 0x8000, v120
	v_lshrrev_b32_e32 v120, 3, v123
	v_and_b32_e32 v121, 7, v123
	v_mul_u32_u24_e32 v123, 0x110, v120
	v_add_u32_e32 v119, v119, v123
	v_lshl_add_u32 v119, v121, 5, v119
	v_readlane_b32 vcc_lo, v248, 4
	v_readlane_b32 vcc_hi, v248, 5
	s_lshl_b32 s0, s3, 12
	s_lshl_b32 s1, s44, 1
	s_add_i32 s0, s0, s1
	s_mul_i32 s10, s3, 0x880
	s_add_i32 s1, s1, s10
	s_add_i32 s1, s1, 0x1699e000
	v_lshrrev_b32_e32 v124, 1, v122
	v_mul_u32_u24_e32 v124, 0x40000, v124
	v_mul_u32_u24_e32 v126, 0x1000, v120
	v_add_u32_e32 v124, v124, v126
	v_and_b32_e32 v126, 1, v122
	v_mul_u32_u24_e32 v126, 0x80, v126
	v_lshl_add_u32 v126, v121, 4, v126
	v_add3_u32 v124, v124, v126, s0
	v_lshrrev_b32_e32 v125, 1, v122
	v_mul_u32_u24_e32 v125, 0x22000, v125
	v_mul_u32_u24_e32 v126, 0x880, v120
	v_add_u32_e32 v125, v125, v126
	v_and_b32_e32 v126, 1, v122
	v_mul_u32_u24_e32 v126, 0x80, v126
	v_lshl_add_u32 v126, v121, 4, v126
	v_add3_u32 v125, v125, v126, s1
	ds_write_b128 v118, v[48:51] offset:0
	ds_write_b128 v118, v[52:55] offset:32
	ds_write_b128 v118, v[56:59] offset:64
	ds_write_b128 v118, v[60:63] offset:96
	ds_write_b128 v118, v[32:35] offset:128
	ds_write_b128 v118, v[36:39] offset:160
	ds_write_b128 v118, v[40:43] offset:192
	ds_write_b128 v118, v[44:47] offset:224
	s_waitcnt lgkmcnt(0)
	global_load_dwordx4 v[84:87], v124, vcc offset:0 nt
	v_add_u32_e32 v124, 0x8000, v124
	global_load_dwordx4 v[88:91], v124, vcc offset:0 nt
	v_add_u32_e32 v124, 0x8000, v124
	global_load_dwordx4 v[92:95], v124, vcc offset:0 nt
	v_add_u32_e32 v124, 0x8000, v124
	global_load_dwordx4 v[96:99], v124, vcc offset:0 nt
	v_add_u32_e32 v124, 0x8000, v124
	ds_read_b128 v[32:35], v119 offset:0
	ds_read_b128 v[36:39], v119 offset:16
	ds_read_b128 v[40:43], v119 offset:2176
	ds_read_b128 v[44:47], v119 offset:2192
	s_waitcnt vmcnt(3) lgkmcnt(2)
	v_lshlrev_b32_e32 v127, 16, v84
	v_mul_f32_e32 v32, v32, v127
	v_and_b32_e32 v127, 0xffff0000, v84
	v_mul_f32_e32 v33, v33, v127
	v_lshlrev_b32_e32 v127, 16, v85
	v_mul_f32_e32 v34, v34, v127
	v_and_b32_e32 v127, 0xffff0000, v85
	v_mul_f32_e32 v35, v35, v127
	v_lshlrev_b32_e32 v127, 16, v86
	v_mul_f32_e32 v36, v36, v127
	v_and_b32_e32 v127, 0xffff0000, v86
	v_mul_f32_e32 v37, v37, v127
	v_lshlrev_b32_e32 v127, 16, v87
	v_mul_f32_e32 v38, v38, v127
	v_and_b32_e32 v127, 0xffff0000, v87
	v_mul_f32_e32 v39, v39, v127
	v_cvt_pk_bf16_f32 v32, v32, v33
	v_cvt_pk_bf16_f32 v33, v34, v35
	v_cvt_pk_bf16_f32 v34, v36, v37
	v_cvt_pk_bf16_f32 v35, v38, v39
	global_store_dwordx4 v125, v[32:35], s[96:97]
	v_add_u32_e32 v125, 0x4400, v125
	s_waitcnt vmcnt(3) lgkmcnt(0)
	v_lshlrev_b32_e32 v127, 16, v88
	v_mul_f32_e32 v40, v40, v127
	v_and_b32_e32 v127, 0xffff0000, v88
	v_mul_f32_e32 v41, v41, v127
	v_lshlrev_b32_e32 v127, 16, v89
	v_mul_f32_e32 v42, v42, v127
	v_and_b32_e32 v127, 0xffff0000, v89
	v_mul_f32_e32 v43, v43, v127
	v_lshlrev_b32_e32 v127, 16, v90
	v_mul_f32_e32 v44, v44, v127
	v_and_b32_e32 v127, 0xffff0000, v90
	v_mul_f32_e32 v45, v45, v127
	v_lshlrev_b32_e32 v127, 16, v91
	v_mul_f32_e32 v46, v46, v127
	v_and_b32_e32 v127, 0xffff0000, v91
	v_mul_f32_e32 v47, v47, v127
	v_cvt_pk_bf16_f32 v40, v40, v41
	v_cvt_pk_bf16_f32 v41, v42, v43
	v_cvt_pk_bf16_f32 v42, v44, v45
	v_cvt_pk_bf16_f32 v43, v46, v47
	global_store_dwordx4 v125, v[40:43], s[96:97]
	v_add_u32_e32 v125, 0x4400, v125
	ds_read_b128 v[32:35], v119 offset:4352
	ds_read_b128 v[36:39], v119 offset:4368
	ds_read_b128 v[40:43], v119 offset:6528
	ds_read_b128 v[44:47], v119 offset:6544
	s_waitcnt vmcnt(3) lgkmcnt(2)
	v_lshlrev_b32_e32 v127, 16, v92
	v_mul_f32_e32 v32, v32, v127
	v_and_b32_e32 v127, 0xffff0000, v92
	v_mul_f32_e32 v33, v33, v127
	v_lshlrev_b32_e32 v127, 16, v93
	v_mul_f32_e32 v34, v34, v127
	v_and_b32_e32 v127, 0xffff0000, v93
	v_mul_f32_e32 v35, v35, v127
	v_lshlrev_b32_e32 v127, 16, v94
	v_mul_f32_e32 v36, v36, v127
	v_and_b32_e32 v127, 0xffff0000, v94
	v_mul_f32_e32 v37, v37, v127
	v_lshlrev_b32_e32 v127, 16, v95
	v_mul_f32_e32 v38, v38, v127
	v_and_b32_e32 v127, 0xffff0000, v95
	v_mul_f32_e32 v39, v39, v127
	v_cvt_pk_bf16_f32 v32, v32, v33
	v_cvt_pk_bf16_f32 v33, v34, v35
	v_cvt_pk_bf16_f32 v34, v36, v37
	v_cvt_pk_bf16_f32 v35, v38, v39
	global_store_dwordx4 v125, v[32:35], s[96:97]
	v_add_u32_e32 v125, 0x4400, v125
	s_waitcnt vmcnt(3) lgkmcnt(0)
	v_lshlrev_b32_e32 v127, 16, v96
	v_mul_f32_e32 v40, v40, v127
	v_and_b32_e32 v127, 0xffff0000, v96
	v_mul_f32_e32 v41, v41, v127
	v_lshlrev_b32_e32 v127, 16, v97
	v_mul_f32_e32 v42, v42, v127
	v_and_b32_e32 v127, 0xffff0000, v97
	v_mul_f32_e32 v43, v43, v127
	v_lshlrev_b32_e32 v127, 16, v98
	v_mul_f32_e32 v44, v44, v127
	v_and_b32_e32 v127, 0xffff0000, v98
	v_mul_f32_e32 v45, v45, v127
	v_lshlrev_b32_e32 v127, 16, v99
	v_mul_f32_e32 v46, v46, v127
	v_and_b32_e32 v127, 0xffff0000, v99
	v_mul_f32_e32 v47, v47, v127
	v_cvt_pk_bf16_f32 v40, v40, v41
	v_cvt_pk_bf16_f32 v41, v42, v43
	v_cvt_pk_bf16_f32 v42, v44, v45
	v_cvt_pk_bf16_f32 v43, v46, v47
	global_store_dwordx4 v125, v[40:43], s[96:97]
	v_add_u32_e32 v125, 0x4400, v125
	ds_write_b128 v118, v[16:19] offset:0
	ds_write_b128 v118, v[20:23] offset:32
	ds_write_b128 v118, v[24:27] offset:64
	ds_write_b128 v118, v[28:31] offset:96
	ds_write_b128 v118, v[0:3] offset:128
	ds_write_b128 v118, v[4:7] offset:160
	ds_write_b128 v118, v[8:11] offset:192
	ds_write_b128 v118, v[12:15] offset:224
	s_waitcnt lgkmcnt(0)
; __device__ __forceinline__ unsigned pk2(float lo, float hi) { f32v2_t v = {lo, hi}; bf16v2_t r = __builtin_convertvector(v, bf16v2_t); return __builtin_bit_cast(unsigned, r); }
; __device__ __forceinline__ float bflo(unsigned w) { return __uint_as_float(w << 16); }
; __device__ __forceinline__ float bfhi(unsigned w) { return __uint_as_float(w & 0xffff0000u); }
; __device__ void phase_merge(const Params& p, char* lds) {
;     ...
;           const int tok = m0 + wr * 64 + i * 32 + l31; const int cb = n0 + wc * 64 + j * 32;
;           const bf16_t* gp = gates + (size_t)tok * 2048 + cb + 4 * hh;
;           bf16_t* op = mg + (size_t)tok * LDH + cb + 4 * hh;
; #pragma unroll
;           for (int g = 0; g < 4; ++g) {
;             const u32x2 gv = *(const u32x2*)(gp + 8 * g);
;             u32x2 w;
;             w.x = pk2(acc[i][j][4 * g] * bflo(gv.x), acc[i][j][4 * g + 1] * bfhi(gv.x));
;             w.y = pk2(acc[i][j][4 * g + 2] * bflo(gv.y), acc[i][j][4 * g + 3] * bfhi(gv.y));
;             *(u32x2*)(op + 8 * g) = w;
;           }
	global_load_dwordx4 v[84:87], v124, vcc offset:0 nt
	v_add_u32_e32 v124, 0x8000, v124
	global_load_dwordx4 v[88:91], v124, vcc offset:0 nt
	v_add_u32_e32 v124, 0x8000, v124
	global_load_dwordx4 v[92:95], v124, vcc offset:0 nt
	v_add_u32_e32 v124, 0x8000, v124
	global_load_dwordx4 v[96:99], v124, vcc offset:0 nt
	v_add_u32_e32 v124, 0x8000, v124
	ds_read_b128 v[0:3], v119 offset:0
	ds_read_b128 v[4:7], v119 offset:16
	ds_read_b128 v[8:11], v119 offset:2176
	ds_read_b128 v[12:15], v119 offset:2192
	s_waitcnt vmcnt(3) lgkmcnt(2)
	v_lshlrev_b32_e32 v127, 16, v84
	v_mul_f32_e32 v0, v0, v127
	v_and_b32_e32 v127, 0xffff0000, v84
	v_mul_f32_e32 v1, v1, v127
	v_lshlrev_b32_e32 v127, 16, v85
	v_mul_f32_e32 v2, v2, v127
	v_and_b32_e32 v127, 0xffff0000, v85
	v_mul_f32_e32 v3, v3, v127
	v_lshlrev_b32_e32 v127, 16, v86
	v_mul_f32_e32 v4, v4, v127
	v_and_b32_e32 v127, 0xffff0000, v86
	v_mul_f32_e32 v5, v5, v127
	v_lshlrev_b32_e32 v127, 16, v87
	v_mul_f32_e32 v6, v6, v127
	v_and_b32_e32 v127, 0xffff0000, v87
	v_mul_f32_e32 v7, v7, v127
	v_cvt_pk_bf16_f32 v0, v0, v1
	v_cvt_pk_bf16_f32 v1, v2, v3
	v_cvt_pk_bf16_f32 v2, v4, v5
	v_cvt_pk_bf16_f32 v3, v6, v7
	global_store_dwordx4 v125, v[0:3], s[96:97]
	v_add_u32_e32 v125, 0x4400, v125
	s_waitcnt vmcnt(3) lgkmcnt(0)
	v_lshlrev_b32_e32 v127, 16, v88
	v_mul_f32_e32 v8, v8, v127
	v_and_b32_e32 v127, 0xffff0000, v88
	v_mul_f32_e32 v9, v9, v127
	v_lshlrev_b32_e32 v127, 16, v89
	v_mul_f32_e32 v10, v10, v127
	v_and_b32_e32 v127, 0xffff0000, v89
	v_mul_f32_e32 v11, v11, v127
	v_lshlrev_b32_e32 v127, 16, v90
	v_mul_f32_e32 v12, v12, v127
	v_and_b32_e32 v127, 0xffff0000, v90
	v_mul_f32_e32 v13, v13, v127
	v_lshlrev_b32_e32 v127, 16, v91
	v_mul_f32_e32 v14, v14, v127
	v_and_b32_e32 v127, 0xffff0000, v91
	v_mul_f32_e32 v15, v15, v127
	v_cvt_pk_bf16_f32 v8, v8, v9
	v_cvt_pk_bf16_f32 v9, v10, v11
	v_cvt_pk_bf16_f32 v10, v12, v13
	v_cvt_pk_bf16_f32 v11, v14, v15
	global_store_dwordx4 v125, v[8:11], s[96:97]
	v_add_u32_e32 v125, 0x4400, v125
	ds_read_b128 v[0:3], v119 offset:4352
	ds_read_b128 v[4:7], v119 offset:4368
	ds_read_b128 v[8:11], v119 offset:6528
	ds_read_b128 v[12:15], v119 offset:6544
	s_waitcnt vmcnt(3) lgkmcnt(2)
	v_lshlrev_b32_e32 v127, 16, v92
	v_mul_f32_e32 v0, v0, v127
	v_and_b32_e32 v127, 0xffff0000, v92
	v_mul_f32_e32 v1, v1, v127
	v_lshlrev_b32_e32 v127, 16, v93
	v_mul_f32_e32 v2, v2, v127
	v_and_b32_e32 v127, 0xffff0000, v93
	v_mul_f32_e32 v3, v3, v127
	v_lshlrev_b32_e32 v127, 16, v94
	v_mul_f32_e32 v4, v4, v127
	v_and_b32_e32 v127, 0xffff0000, v94
	v_mul_f32_e32 v5, v5, v127
	v_lshlrev_b32_e32 v127, 16, v95
	v_mul_f32_e32 v6, v6, v127
	v_and_b32_e32 v127, 0xffff0000, v95
	v_mul_f32_e32 v7, v7, v127
	v_cvt_pk_bf16_f32 v0, v0, v1
	v_cvt_pk_bf16_f32 v1, v2, v3
	v_cvt_pk_bf16_f32 v2, v4, v5
	v_cvt_pk_bf16_f32 v3, v6, v7
	global_store_dwordx4 v125, v[0:3], s[96:97]
	v_add_u32_e32 v125, 0x4400, v125
	s_waitcnt vmcnt(3) lgkmcnt(0)
; __device__ __forceinline__ unsigned pk2(float lo, float hi) { f32v2_t v = {lo, hi}; bf16v2_t r = __builtin_convertvector(v, bf16v2_t); return __builtin_bit_cast(unsigned, r); }
; __device__ __forceinline__ float bflo(unsigned w) { return __uint_as_float(w << 16); }
; __device__ __forceinline__ float bfhi(unsigned w) { return __uint_as_float(w & 0xffff0000u); }
; template <bool SW>
; __device__ __forceinline__ void gemm_mainloop(const bf16_t* __restrict__ A, int lda, const bf16_t* __restrict__ Bt, int ldb, int K,
;                                               f32x16 (&acc)[2][2], char* lds, int kstart) {
;     ...
;   for (int i = 0; i < 4; ++i) {
;     const int row = lrow + 8 * i; const int ch = (lane & 7) ^ ((row >> 1) & 7);
;     ap[i] = A + (size_t)row * lda + ch * 8; bp[i] = Bt + (size_t)row * ldb + ch * 8;
;   }
;   char* ldst = lds + (wid * 32) * 128 + lane * 16;
; #pragma unroll
;   for (int i = 0; i < 4; ++i) { glds16(ap[i] + kstart * 64, ldst + i * 1024); glds16(bp[i] + kstart * 64, ldst + 16384 + i * 1024); }
;   asm volatile("s_waitcnt vmcnt(0)" ::: "memory");
;   __syncthreads();
; __device__ void phase_merge(const Params& p, char* lds) {
;     ...
;             w.x = pk2(acc[i][j][4 * g] * bflo(gv.x), acc[i][j][4 * g + 1] * bfhi(gv.x));
;             w.y = pk2(acc[i][j][4 * g + 2] * bflo(gv.y), acc[i][j][4 * g + 3] * bfhi(gv.y));
;             *(u32x2*)(op + 8 * g) = w;
	v_lshlrev_b32_e32 v127, 16, v96
	v_mul_f32_e32 v8, v8, v127
	v_and_b32_e32 v127, 0xffff0000, v96
	v_mul_f32_e32 v9, v9, v127
	v_lshlrev_b32_e32 v127, 16, v97
	v_mul_f32_e32 v10, v10, v127
	v_and_b32_e32 v127, 0xffff0000, v97
	v_mul_f32_e32 v11, v11, v127
	v_lshlrev_b32_e32 v127, 16, v98
	v_mul_f32_e32 v12, v12, v127
	v_and_b32_e32 v127, 0xffff0000, v98
	v_mul_f32_e32 v13, v13, v127
	v_lshlrev_b32_e32 v127, 16, v99
	v_mul_f32_e32 v14, v14, v127
	v_and_b32_e32 v127, 0xffff0000, v99
	v_mul_f32_e32 v15, v15, v127
	v_cvt_pk_bf16_f32 v8, v8, v9
	v_cvt_pk_bf16_f32 v9, v10, v11
	v_cvt_pk_bf16_f32 v10, v12, v13
	v_cvt_pk_bf16_f32 v11, v14, v15
	global_store_dwordx4 v125, v[8:11], s[96:97]
	v_add_u32_e32 v125, 0x4400, v125
	v_mov_b32_e32 v77, v65
	v_mov_b32_e32 v79, v65
	s_add_u32 s0, s24, s38
	s_addc_u32 s1, s25, s39
	s_add_u32 s38, s26, s40
	s_addc_u32 s39, s27, s41
	s_lshl_b32 s10, s43, 1
	v_lshl_add_u64 v[0:1], s[0:1], 0, v[64:65]
	v_lshl_add_u64 v[86:87], v[0:1], 0, v[76:77]
	v_lshl_add_u64 v[0:1], s[38:39], 0, v[64:65]
	v_lshl_add_u64 v[88:89], v[0:1], 0, v[76:77]
	v_lshl_add_u64 v[0:1], s[0:1], 0, v[70:71]
	v_lshl_add_u64 v[90:91], v[0:1], 0, v[78:79]
	v_lshl_add_u64 v[0:1], s[38:39], 0, v[70:71]
	v_lshl_add_u64 v[92:93], v[0:1], 0, v[78:79]
	v_lshl_add_u64 v[0:1], s[0:1], 0, v[72:73]
	v_lshl_add_u64 v[94:95], v[0:1], 0, v[76:77]
	v_lshl_add_u64 v[0:1], s[38:39], 0, v[72:73]
	v_lshl_add_u64 v[96:97], v[0:1], 0, v[76:77]
	v_lshl_add_u64 v[0:1], s[0:1], 0, v[74:75]
	v_lshl_add_u64 v[98:99], v[0:1], 0, v[78:79]
	v_lshl_add_u64 v[0:1], s[38:39], 0, v[74:75]
	v_readfirstlane_b32 s0, v102
	v_lshl_add_u64 v[100:101], v[0:1], 0, v[78:79]
	v_lshl_add_u64 v[0:1], v[86:87], 0, s[10:11]
	s_mov_b32 m0, s0
	v_readfirstlane_b32 s0, v111
	global_load_lds_dwordx4 v[0:1], off
	v_lshl_add_u64 v[0:1], v[88:89], 0, s[10:11]
	s_mov_b32 m0, s0
	v_readfirstlane_b32 s0, v112
	global_load_lds_dwordx4 v[0:1], off
	v_lshl_add_u64 v[0:1], v[90:91], 0, s[10:11]
	s_mov_b32 m0, s0
	v_readfirstlane_b32 s0, v113
	global_load_lds_dwordx4 v[0:1], off
	v_lshl_add_u64 v[0:1], v[92:93], 0, s[10:11]
	s_mov_b32 m0, s0
	v_readfirstlane_b32 s0, v114
	global_load_lds_dwordx4 v[0:1], off
	v_lshl_add_u64 v[0:1], v[94:95], 0, s[10:11]
	s_mov_b32 m0, s0
	v_readfirstlane_b32 s0, v115
	global_load_lds_dwordx4 v[0:1], off
	v_lshl_add_u64 v[0:1], v[96:97], 0, s[10:11]
	s_mov_b32 m0, s0
	v_readfirstlane_b32 s0, v116
	global_load_lds_dwordx4 v[0:1], off
	v_lshl_add_u64 v[0:1], v[98:99], 0, s[10:11]
	s_mov_b32 m0, s0
	v_readfirstlane_b32 s0, v117
	global_load_lds_dwordx4 v[0:1], off
	v_lshl_add_u64 v[0:1], v[100:101], 0, s[10:11]
	s_mov_b32 m0, s0
	s_mov_b32 s39, 0
	global_load_lds_dwordx4 v[0:1], off
	v_mov_b32_e32 v0, 0
	s_mov_b32 s38, 0
	v_mov_b32_e32 v1, v0
	v_mov_b32_e32 v2, v0
	v_mov_b32_e32 v3, v0
	v_mov_b32_e32 v4, v0
	v_mov_b32_e32 v5, v0
	v_mov_b32_e32 v6, v0
	v_mov_b32_e32 v7, v0
	v_mov_b32_e32 v8, v0
	v_mov_b32_e32 v9, v0
	v_mov_b32_e32 v10, v0
	v_mov_b32_e32 v11, v0
	v_mov_b32_e32 v12, v0
	v_mov_b32_e32 v13, v0
	v_mov_b32_e32 v14, v0
	v_mov_b32_e32 v15, v0
	v_mov_b32_e32 v16, v0
	v_mov_b32_e32 v17, v0
	v_mov_b32_e32 v18, v0
	v_mov_b32_e32 v19, v0
	v_mov_b32_e32 v20, v0
	v_mov_b32_e32 v21, v0
	v_mov_b32_e32 v22, v0
	v_mov_b32_e32 v23, v0
	v_mov_b32_e32 v24, v0
	v_mov_b32_e32 v25, v0
	v_mov_b32_e32 v26, v0
	v_mov_b32_e32 v27, v0
	v_mov_b32_e32 v28, v0
	v_mov_b32_e32 v29, v0
	v_mov_b32_e32 v30, v0
	v_mov_b32_e32 v31, v0
	v_mov_b32_e32 v32, v0
	v_mov_b32_e32 v33, v0
	v_mov_b32_e32 v34, v0
	v_mov_b32_e32 v35, v0
	v_mov_b32_e32 v36, v0
	v_mov_b32_e32 v37, v0
	v_mov_b32_e32 v38, v0
	v_mov_b32_e32 v39, v0
	v_mov_b32_e32 v40, v0
	v_mov_b32_e32 v41, v0
	v_mov_b32_e32 v42, v0
	v_mov_b32_e32 v43, v0
	v_mov_b32_e32 v44, v0
	v_mov_b32_e32 v45, v0
	v_mov_b32_e32 v46, v0
	v_mov_b32_e32 v47, v0
	v_mov_b32_e32 v48, v0
	v_mov_b32_e32 v49, v0
	v_mov_b32_e32 v50, v0
	v_mov_b32_e32 v51, v0
	v_mov_b32_e32 v52, v0
	v_mov_b32_e32 v53, v0
	v_mov_b32_e32 v54, v0
	v_mov_b32_e32 v55, v0
	v_mov_b32_e32 v56, v0
	v_mov_b32_e32 v57, v0
	v_mov_b32_e32 v58, v0
	v_mov_b32_e32 v59, v0
	v_mov_b32_e32 v60, v0
	v_mov_b32_e32 v61, v0
	v_mov_b32_e32 v62, v0
	v_mov_b32_e32 v63, v0
	s_waitcnt vmcnt(0) lgkmcnt(0)
	s_barrier
	s_branch .LBB0_796

; __device__ void phase_outproj(const Params& p, char* lds) {
;     ...
;         const int tok = m0 + wr * 64 + i * 32 + l31; const int cb = n0 + wc * 64 + j * 32 + 4 * hh;
;         const float* xr = ((tok < TP) ? p.in[0] + (size_t)tok * 1024 : p.in[1] + (size_t)(tok - TP) * 1024) + cb;
;         float* orow = x1 + (size_t)tok * 1024 + cb;
; #pragma unroll
;         for (int g = 0; g < 4; ++g) {
;           const f32x4 xv = *(const f32x4*)(xr + 8 * g);
;           f32x4 w = {xv[0] + acc[i][j][4 * g], xv[1] + acc[i][j][4 * g + 1], xv[2] + acc[i][j][4 * g + 2], xv[3] + acc[i][j][4 * g + 3]};
;           *(f32x4*)(orow + 8 * g) = w;
;         }
.LBB0_869:
	v_and_b32_e32 v117, 63, v181
	v_lshrrev_b32_e32 v116, 6, v181
	v_and_b32_e32 v112, 31, v117
	v_lshrrev_b32_e32 v113, 5, v117
	v_mul_u32_u24_e32 v112, 0x110, v112
	v_lshlrev_b32_e32 v113, 4, v113
	v_mul_u32_u24_e32 v114, 0x2200, v116
	v_add3_u32 v112, v112, v113, v114
	v_add_u32_e32 v112, 0x8000, v112
	v_add_u32_e32 v113, 0x8000, v114
	v_lshrrev_b32_e32 v114, 4, v117
	v_and_b32_e32 v115, 15, v117
	v_mul_u32_u24_e32 v117, 0x110, v114
	v_add_u32_e32 v113, v113, v117
	v_lshl_add_u32 v113, v115, 4, v113
	s_cmp_lt_i32 s3, 0x8000
	s_cselect_b32 vcc_lo, s52, s54
	s_cselect_b32 vcc_hi, s53, s55
	s_cselect_b32 s0, 0, 0x8000
	s_sub_i32 s0, s3, s0
	s_lshl_b32 s0, s0, 12
	s_lshl_b32 s12, s38, 2
	s_add_i32 s0, s0, s12
	s_lshl_b32 s1, s3, 12
	s_add_i32 s1, s1, s12
	s_add_i32 s1, s1, 0xa08e000
	v_lshrrev_b32_e32 v118, 1, v116
	v_mul_u32_u24_e32 v118, 0x40000, v118
	v_mul_u32_u24_e32 v120, 0x1000, v114
	v_add_u32_e32 v118, v118, v120
	v_and_b32_e32 v120, 1, v116
	v_mul_u32_u24_e32 v120, 0x100, v120
	v_lshl_add_u32 v120, v115, 4, v120
	v_add3_u32 v118, v118, v120, s0
	v_lshrrev_b32_e32 v119, 1, v116
	v_mul_u32_u24_e32 v119, 0x40000, v119
	v_mul_u32_u24_e32 v120, 0x1000, v114
	v_add_u32_e32 v119, v119, v120
	v_and_b32_e32 v120, 1, v116
	v_mul_u32_u24_e32 v120, 0x100, v120
	v_lshl_add_u32 v120, v115, 4, v120
	v_add3_u32 v119, v119, v120, s1
	ds_write_b128 v112, v[48:51] offset:0
	ds_write_b128 v112, v[52:55] offset:32
	ds_write_b128 v112, v[56:59] offset:64
	ds_write_b128 v112, v[60:63] offset:96
	ds_write_b128 v112, v[32:35] offset:128
	ds_write_b128 v112, v[36:39] offset:160
	ds_write_b128 v112, v[40:43] offset:192
	ds_write_b128 v112, v[44:47] offset:224
	s_waitcnt lgkmcnt(0)
	global_load_dwordx4 v[80:83], v118, vcc nt
	v_add_u32_e32 v118, 0x4000, v118
	global_load_dwordx4 v[84:87], v118, vcc nt
	v_add_u32_e32 v118, 0x4000, v118
	global_load_dwordx4 v[88:91], v118, vcc nt
	v_add_u32_e32 v118, 0x4000, v118
	global_load_dwordx4 v[92:95], v118, vcc nt
	v_add_u32_e32 v118, 0x4000, v118
	ds_read_b128 v[32:35], v113 offset:0
	ds_read_b128 v[36:39], v113 offset:1088
	ds_read_b128 v[40:43], v113 offset:2176
	ds_read_b128 v[44:47], v113 offset:3264
	s_waitcnt vmcnt(3) lgkmcnt(3)
	v_add_f32_e32 v32, v32, v80
	v_add_f32_e32 v33, v33, v81
	v_add_f32_e32 v34, v34, v82
	v_add_f32_e32 v35, v35, v83
	global_store_dwordx4 v119, v[32:35], s[96:97]
	v_add_u32_e32 v119, 0x4000, v119
	s_waitcnt vmcnt(3) lgkmcnt(2)
	v_add_f32_e32 v36, v36, v84
	v_add_f32_e32 v37, v37, v85
	v_add_f32_e32 v38, v38, v86
	v_add_f32_e32 v39, v39, v87
	global_store_dwordx4 v119, v[36:39], s[96:97]
	v_add_u32_e32 v119, 0x4000, v119
	s_waitcnt vmcnt(3) lgkmcnt(1)
	v_add_f32_e32 v40, v40, v88
	v_add_f32_e32 v41, v41, v89
	v_add_f32_e32 v42, v42, v90
	v_add_f32_e32 v43, v43, v91
	global_store_dwordx4 v119, v[40:43], s[96:97]
	v_add_u32_e32 v119, 0x4000, v119
	s_waitcnt vmcnt(3) lgkmcnt(0)
	v_add_f32_e32 v44, v44, v92
	v_add_f32_e32 v45, v45, v93
	v_add_f32_e32 v46, v46, v94
	v_add_f32_e32 v47, v47, v95
	global_store_dwordx4 v119, v[44:47], s[96:97]
	v_add_u32_e32 v119, 0x4000, v119
	global_load_dwordx4 v[80:83], v118, vcc nt
	v_add_u32_e32 v118, 0x4000, v118
	global_load_dwordx4 v[84:87], v118, vcc nt
	v_add_u32_e32 v118, 0x4000, v118
	global_load_dwordx4 v[88:91], v118, vcc nt
	v_add_u32_e32 v118, 0x4000, v118
	global_load_dwordx4 v[92:95], v118, vcc nt
	v_add_u32_e32 v118, 0x4000, v118
	ds_read_b128 v[32:35], v113 offset:4352
	ds_read_b128 v[36:39], v113 offset:5440
	ds_read_b128 v[40:43], v113 offset:6528
	ds_read_b128 v[44:47], v113 offset:7616
	s_waitcnt vmcnt(3) lgkmcnt(3)
	v_add_f32_e32 v32, v32, v80
	v_add_f32_e32 v33, v33, v81
	v_add_f32_e32 v34, v34, v82
	v_add_f32_e32 v35, v35, v83
	global_store_dwordx4 v119, v[32:35], s[96:97]
	v_add_u32_e32 v119, 0x4000, v119
	s_waitcnt vmcnt(3) lgkmcnt(2)
; __device__ void phase_outproj(const Params& p, char* lds) {
;     ...
;     int mt, nt; if (!tile_at(260, 8, it, mt, nt)) break;
;     ...
;         const int tok = m0 + wr * 64 + i * 32 + l31; const int cb = n0 + wc * 64 + j * 32 + 4 * hh;
;         const float* xr = ((tok < TP) ? p.in[0] + (size_t)tok * 1024 : p.in[1] + (size_t)(tok - TP) * 1024) + cb;
;         float* orow = x1 + (size_t)tok * 1024 + cb;
; #pragma unroll
;         for (int g = 0; g < 4; ++g) {
;           const f32x4 xv = *(const f32x4*)(xr + 8 * g);
;           f32x4 w = {xv[0] + acc[i][j][4 * g], xv[1] + acc[i][j][4 * g + 1], xv[2] + acc[i][j][4 * g + 2], xv[3] + acc[i][j][4 * g + 3]};
;           *(f32x4*)(orow + 8 * g) = w;
;         }
	v_add_f32_e32 v36, v36, v84
	v_add_f32_e32 v37, v37, v85
	v_add_f32_e32 v38, v38, v86
	v_add_f32_e32 v39, v39, v87
	global_store_dwordx4 v119, v[36:39], s[96:97]
	v_add_u32_e32 v119, 0x4000, v119
	s_waitcnt vmcnt(3) lgkmcnt(1)
	v_add_f32_e32 v40, v40, v88
	v_add_f32_e32 v41, v41, v89
	v_add_f32_e32 v42, v42, v90
	v_add_f32_e32 v43, v43, v91
	global_store_dwordx4 v119, v[40:43], s[96:97]
	v_add_u32_e32 v119, 0x4000, v119
	s_waitcnt vmcnt(3) lgkmcnt(0)
	v_add_f32_e32 v44, v44, v92
	v_add_f32_e32 v45, v45, v93
	v_add_f32_e32 v46, v46, v94
	v_add_f32_e32 v47, v47, v95
	global_store_dwordx4 v119, v[44:47], s[96:97]
	v_add_u32_e32 v119, 0x4000, v119
	ds_write_b128 v112, v[16:19] offset:0
	ds_write_b128 v112, v[20:23] offset:32
	ds_write_b128 v112, v[24:27] offset:64
	ds_write_b128 v112, v[28:31] offset:96
	ds_write_b128 v112, v[0:3] offset:128
	ds_write_b128 v112, v[4:7] offset:160
	ds_write_b128 v112, v[8:11] offset:192
	ds_write_b128 v112, v[12:15] offset:224
	s_waitcnt lgkmcnt(0)
	global_load_dwordx4 v[80:83], v118, vcc nt
	v_add_u32_e32 v118, 0x4000, v118
	global_load_dwordx4 v[84:87], v118, vcc nt
	v_add_u32_e32 v118, 0x4000, v118
	global_load_dwordx4 v[88:91], v118, vcc nt
	v_add_u32_e32 v118, 0x4000, v118
	global_load_dwordx4 v[92:95], v118, vcc nt
	v_add_u32_e32 v118, 0x4000, v118
	ds_read_b128 v[0:3], v113 offset:0
	ds_read_b128 v[4:7], v113 offset:1088
	ds_read_b128 v[8:11], v113 offset:2176
	ds_read_b128 v[12:15], v113 offset:3264
	s_waitcnt vmcnt(3) lgkmcnt(3)
	v_add_f32_e32 v0, v0, v80
	v_add_f32_e32 v1, v1, v81
	v_add_f32_e32 v2, v2, v82
	v_add_f32_e32 v3, v3, v83
	global_store_dwordx4 v119, v[0:3], s[96:97]
	v_add_u32_e32 v119, 0x4000, v119
	s_waitcnt vmcnt(3) lgkmcnt(2)
	v_add_f32_e32 v4, v4, v84
	v_add_f32_e32 v5, v5, v85
	v_add_f32_e32 v6, v6, v86
	v_add_f32_e32 v7, v7, v87
	global_store_dwordx4 v119, v[4:7], s[96:97]
	v_add_u32_e32 v119, 0x4000, v119
	s_waitcnt vmcnt(3) lgkmcnt(1)
	v_add_f32_e32 v8, v8, v88
	v_add_f32_e32 v9, v9, v89
	v_add_f32_e32 v10, v10, v90
	v_add_f32_e32 v11, v11, v91
	global_store_dwordx4 v119, v[8:11], s[96:97]
	v_add_u32_e32 v119, 0x4000, v119
	s_waitcnt vmcnt(3) lgkmcnt(0)
	v_add_f32_e32 v12, v12, v92
	v_add_f32_e32 v13, v13, v93
	v_add_f32_e32 v14, v14, v94
	v_add_f32_e32 v15, v15, v95
	global_store_dwordx4 v119, v[12:15], s[96:97]
	v_add_u32_e32 v119, 0x4000, v119
	global_load_dwordx4 v[80:83], v118, vcc nt
	v_add_u32_e32 v118, 0x4000, v118
	global_load_dwordx4 v[84:87], v118, vcc nt
	v_add_u32_e32 v118, 0x4000, v118
	global_load_dwordx4 v[88:91], v118, vcc nt
	v_add_u32_e32 v118, 0x4000, v118
	global_load_dwordx4 v[92:95], v118, vcc nt
	v_add_u32_e32 v118, 0x4000, v118
	ds_read_b128 v[0:3], v113 offset:4352
	ds_read_b128 v[4:7], v113 offset:5440
	ds_read_b128 v[8:11], v113 offset:6528
	ds_read_b128 v[12:15], v113 offset:7616
	s_waitcnt vmcnt(3) lgkmcnt(3)
	v_add_f32_e32 v0, v0, v80
	v_add_f32_e32 v1, v1, v81
	v_add_f32_e32 v2, v2, v82
	v_add_f32_e32 v3, v3, v83
	global_store_dwordx4 v119, v[0:3], s[96:97]
	v_add_u32_e32 v119, 0x4000, v119
	s_waitcnt vmcnt(3) lgkmcnt(2)
	v_add_f32_e32 v4, v4, v84
	v_add_f32_e32 v5, v5, v85
	v_add_f32_e32 v6, v6, v86
	v_add_f32_e32 v7, v7, v87
	global_store_dwordx4 v119, v[4:7], s[96:97]
	v_add_u32_e32 v119, 0x4000, v119
	s_waitcnt vmcnt(3) lgkmcnt(1)
	v_add_f32_e32 v8, v8, v88
	v_add_f32_e32 v9, v9, v89
	v_add_f32_e32 v10, v10, v90
	v_add_f32_e32 v11, v11, v91
	global_store_dwordx4 v119, v[8:11], s[96:97]
	v_add_u32_e32 v119, 0x4000, v119
	s_waitcnt vmcnt(3) lgkmcnt(0)
	v_add_f32_e32 v12, v12, v92
	v_add_f32_e32 v13, v13, v93
	v_add_f32_e32 v14, v14, v94
	v_add_f32_e32 v15, v15, v95
	global_store_dwordx4 v119, v[12:15], s[96:97]
	v_add_u32_e32 v119, 0x4000, v119
	s_add_i32 s2, s2, 1
	s_mul_i32 s0, s2, s18
	s_add_i32 s0, s0, s17
	s_cmp_lt_i32 s0, s72
	s_cbranch_scc0 .LBB0_876
